# m0 wait states before LDS-DMAs in the int8 K-loops filled with the segment's own ds_reads instead of s_nop
# baseline (speedup 1.0000x reference)
.LBB0_1238:
	s_add_i32 s74, s38, 2
	s_add_u32 s39, s36, 0xfff80080
	s_addc_u32 s40, s37, -1
	s_cmp_eq_u32 s71, s38
	s_cselect_b32 s41, s67, s40
	s_cselect_b32 s40, s68, s39
	ds_read_b128 v[140:143], v177
	ds_read_b128 v[144:147], v177 offset:1024
	ds_read_b128 v[148:151], v177 offset:2048
	ds_read_b128 v[152:155], v177 offset:3072
	ds_read_b128 v[156:159], v177 offset:16384
	ds_read_b128 v[160:163], v177 offset:17408
	ds_read_b128 v[164:167], v177 offset:18432
	ds_read_b128 v[168:171], v177 offset:19456
	s_cselect_b32 s38, s70, s72
	s_cselect_b32 s39, s69, s73
	s_add_i32 m0, s45, 0xc000
	ds_read_b128 v[180:183], v178
	ds_read_b128 v[184:187], v178 offset:1024
	ds_read_b128 v[188:191], v178 offset:2048
	ds_read_b128 v[192:195], v178 offset:3072
	ds_read_b128 v[196:199], v178 offset:4096
	ds_read_b128 v[200:203], v178 offset:5120
	ds_read_b128 v[204:207], v178 offset:6144
	global_load_lds_dwordx4 v136, s[36:37]
	s_add_i32 m0, s45, 0xe000
	ds_read_b128 v[208:211], v178 offset:7168
	global_load_lds_dwordx4 v138, s[36:37]
	s_waitcnt vmcnt(8)
	s_waitcnt lgkmcnt(0)
	s_barrier
	s_setprio 1
	s_waitcnt lgkmcnt(0)
	v_mfma_i32_16x16x64_i8 v[124:127], v[140:143], v[180:183], v[124:127]
	v_mfma_i32_16x16x64_i8 v[120:123], v[148:151], v[180:183], v[120:123]
	v_mfma_i32_16x16x64_i8 v[116:119], v[140:143], v[188:191], v[116:119]
	v_mfma_i32_16x16x64_i8 v[112:115], v[148:151], v[188:191], v[112:115]
	v_mfma_i32_16x16x64_i8 v[104:107], v[140:143], v[196:199], v[104:107]
	v_mfma_i32_16x16x64_i8 v[96:99], v[148:151], v[196:199], v[96:99]
	v_mfma_i32_16x16x64_i8 v[88:91], v[140:143], v[204:207], v[88:91]
	v_mfma_i32_16x16x64_i8 v[80:83], v[148:151], v[204:207], v[80:83]
	v_mfma_i32_16x16x64_i8 v[124:127], v[144:147], v[184:187], v[124:127]
	v_mfma_i32_16x16x64_i8 v[120:123], v[152:155], v[184:187], v[120:123]
	v_mfma_i32_16x16x64_i8 v[116:119], v[144:147], v[192:195], v[116:119]
	v_mfma_i32_16x16x64_i8 v[112:115], v[152:155], v[192:195], v[112:115]
	v_mfma_i32_16x16x64_i8 v[104:107], v[144:147], v[200:203], v[104:107]
	v_mfma_i32_16x16x64_i8 v[96:99], v[152:155], v[200:203], v[96:99]
	v_mfma_i32_16x16x64_i8 v[88:91], v[144:147], v[208:211], v[88:91]
	v_mfma_i32_16x16x64_i8 v[80:83], v[152:155], v[208:211], v[80:83]
	s_setprio 0
	s_setprio 1
	v_mfma_i32_16x16x64_i8 v[108:111], v[156:159], v[180:183], v[108:111]
	v_mfma_i32_16x16x64_i8 v[100:103], v[164:167], v[180:183], v[100:103]
	v_mfma_i32_16x16x64_i8 v[92:95], v[156:159], v[188:191], v[92:95]
	v_mfma_i32_16x16x64_i8 v[84:87], v[164:167], v[188:191], v[84:87]
	v_mfma_i32_16x16x64_i8 v[76:79], v[156:159], v[196:199], v[76:79]
	v_mfma_i32_16x16x64_i8 v[72:75], v[164:167], v[196:199], v[72:75]
	v_mfma_i32_16x16x64_i8 v[68:71], v[156:159], v[204:207], v[68:71]
	v_mfma_i32_16x16x64_i8 v[64:67], v[164:167], v[204:207], v[64:67]
	v_mfma_i32_16x16x64_i8 v[108:111], v[160:163], v[184:187], v[108:111]
	v_mfma_i32_16x16x64_i8 v[100:103], v[168:171], v[184:187], v[100:103]
	v_mfma_i32_16x16x64_i8 v[92:95], v[160:163], v[192:195], v[92:95]
	v_mfma_i32_16x16x64_i8 v[84:87], v[168:171], v[192:195], v[84:87]
	v_mfma_i32_16x16x64_i8 v[76:79], v[160:163], v[200:203], v[76:79]
	v_mfma_i32_16x16x64_i8 v[72:75], v[168:171], v[200:203], v[72:75]
	v_mfma_i32_16x16x64_i8 v[68:71], v[160:163], v[208:211], v[68:71]
	v_mfma_i32_16x16x64_i8 v[64:67], v[168:171], v[208:211], v[64:67]
	s_setprio 0
	s_barrier
	s_add_i32 s75, s55, s42
	s_mov_b32 m0, s75
	ds_read_b128 v[180:183], v178 offset:16384
	ds_read_b128 v[184:187], v178 offset:17408
	ds_read_b128 v[188:191], v178 offset:18432
	ds_read_b128 v[192:195], v178 offset:19456
	global_load_lds_dwordx4 v130, s[38:39]
	s_add_i32 m0, s75, 0x2000
	s_add_u32 s76, s38, 0x80000
	s_addc_u32 s77, s39, 0
	s_add_i32 s75, s60, s42
	global_load_lds_dwordx4 v134, s[38:39]
	s_mov_b32 m0, s75
	ds_read_b128 v[208:211], v178 offset:23552
	global_load_lds_dwordx4 v130, s[76:77]
	s_add_i32 m0, s75, 0x2000
	ds_read_b128 v[204:207], v178 offset:22528
	global_load_lds_dwordx4 v134, s[76:77]
	s_mov_b32 m0, s45
	ds_read_b128 v[200:203], v178 offset:21504
	global_load_lds_dwordx4 v128, s[40:41]
	s_mov_b32 m0, s46
	ds_read_b128 v[196:199], v178 offset:20480
	global_load_lds_dwordx4 v132, s[40:41]
	s_waitcnt vmcnt(8)
	s_waitcnt lgkmcnt(0)
	s_barrier
	s_setprio 1
	s_waitcnt lgkmcnt(0)
	v_mfma_i32_16x16x64_i8 v[60:63], v[140:143], v[180:183], v[60:63]
	v_mfma_i32_16x16x64_i8 v[56:59], v[148:151], v[180:183], v[56:59]
	v_mfma_i32_16x16x64_i8 v[52:55], v[140:143], v[188:191], v[52:55]
	v_mfma_i32_16x16x64_i8 v[48:51], v[148:151], v[188:191], v[48:51]
	v_mfma_i32_16x16x64_i8 v[40:43], v[140:143], v[196:199], v[40:43]
	v_mfma_i32_16x16x64_i8 v[32:35], v[148:151], v[196:199], v[32:35]
	v_mfma_i32_16x16x64_i8 v[24:27], v[140:143], v[204:207], v[24:27]
	v_mfma_i32_16x16x64_i8 v[16:19], v[148:151], v[204:207], v[16:19]
	v_mfma_i32_16x16x64_i8 v[60:63], v[144:147], v[184:187], v[60:63]
	v_mfma_i32_16x16x64_i8 v[56:59], v[152:155], v[184:187], v[56:59]
	v_mfma_i32_16x16x64_i8 v[52:55], v[144:147], v[192:195], v[52:55]
	v_mfma_i32_16x16x64_i8 v[48:51], v[152:155], v[192:195], v[48:51]
	v_mfma_i32_16x16x64_i8 v[40:43], v[144:147], v[200:203], v[40:43]
	v_mfma_i32_16x16x64_i8 v[32:35], v[152:155], v[200:203], v[32:35]
	v_mfma_i32_16x16x64_i8 v[24:27], v[144:147], v[208:211], v[24:27]
	v_mfma_i32_16x16x64_i8 v[16:19], v[152:155], v[208:211], v[16:19]
	s_setprio 0
	s_setprio 1
	v_mfma_i32_16x16x64_i8 v[44:47], v[156:159], v[180:183], v[44:47]
	v_mfma_i32_16x16x64_i8 v[36:39], v[164:167], v[180:183], v[36:39]
	v_mfma_i32_16x16x64_i8 v[28:31], v[156:159], v[188:191], v[28:31]
	v_mfma_i32_16x16x64_i8 v[20:23], v[164:167], v[188:191], v[20:23]
	v_mfma_i32_16x16x64_i8 v[12:15], v[156:159], v[196:199], v[12:15]
	v_mfma_i32_16x16x64_i8 v[8:11], v[164:167], v[196:199], v[8:11]
	v_mfma_i32_16x16x64_i8 v[4:7], v[156:159], v[204:207], v[4:7]
	v_mfma_i32_16x16x64_i8 v[0:3], v[164:167], v[204:207], v[0:3]
	v_mfma_i32_16x16x64_i8 v[44:47], v[160:163], v[184:187], v[44:47]
	v_mfma_i32_16x16x64_i8 v[36:39], v[168:171], v[184:187], v[36:39]
	v_mfma_i32_16x16x64_i8 v[28:31], v[160:163], v[192:195], v[28:31]
	v_mfma_i32_16x16x64_i8 v[20:23], v[168:171], v[192:195], v[20:23]
	v_mfma_i32_16x16x64_i8 v[12:15], v[160:163], v[200:203], v[12:15]
	v_mfma_i32_16x16x64_i8 v[8:11], v[168:171], v[200:203], v[8:11]
	v_mfma_i32_16x16x64_i8 v[4:7], v[160:163], v[208:211], v[4:7]
	v_mfma_i32_16x16x64_i8 v[0:3], v[168:171], v[208:211], v[0:3]
	s_setprio 0
	s_barrier
	s_add_i32 s75, 0, 0x18000
	s_add_i32 s76, 0, 0x1c000
	ds_read_b128 v[140:143], v177 offset:32768
	ds_read_b128 v[144:147], v177 offset:33792
	ds_read_b128 v[148:151], v177 offset:34816
	ds_read_b128 v[152:155], v177 offset:35840
	ds_read_b128 v[156:159], v177 offset:49152
	ds_read_b128 v[160:163], v177 offset:50176
	ds_read_b128 v[164:167], v177 offset:51200
	ds_read_b128 v[168:171], v177 offset:52224
	s_add_u32 s40, s40, 0x80000
	s_addc_u32 s41, s41, 0
	s_mov_b32 m0, s47
	ds_read_b128 v[180:183], v178 offset:32768
	ds_read_b128 v[184:187], v178 offset:33792
	ds_read_b128 v[188:191], v178 offset:34816
	ds_read_b128 v[192:195], v178 offset:35840
	ds_read_b128 v[196:199], v178 offset:36864
	ds_read_b128 v[200:203], v178 offset:37888
	ds_read_b128 v[204:207], v178 offset:38912
	global_load_lds_dwordx4 v128, s[40:41]
	s_mov_b32 m0, s48
	ds_read_b128 v[208:211], v178 offset:39936
	global_load_lds_dwordx4 v132, s[40:41]
	s_waitcnt vmcnt(8)
	s_waitcnt lgkmcnt(0)
	s_barrier
	s_setprio 1
	s_waitcnt lgkmcnt(0)
	v_mfma_i32_16x16x64_i8 v[124:127], v[140:143], v[180:183], v[124:127]
	v_mfma_i32_16x16x64_i8 v[120:123], v[148:151], v[180:183], v[120:123]
	v_mfma_i32_16x16x64_i8 v[116:119], v[140:143], v[188:191], v[116:119]
	v_mfma_i32_16x16x64_i8 v[112:115], v[148:151], v[188:191], v[112:115]
	v_mfma_i32_16x16x64_i8 v[104:107], v[140:143], v[196:199], v[104:107]
	v_mfma_i32_16x16x64_i8 v[96:99], v[148:151], v[196:199], v[96:99]
	v_mfma_i32_16x16x64_i8 v[88:91], v[140:143], v[204:207], v[88:91]
	v_mfma_i32_16x16x64_i8 v[80:83], v[148:151], v[204:207], v[80:83]
	v_mfma_i32_16x16x64_i8 v[124:127], v[144:147], v[184:187], v[124:127]
	v_mfma_i32_16x16x64_i8 v[120:123], v[152:155], v[184:187], v[120:123]
	v_mfma_i32_16x16x64_i8 v[116:119], v[144:147], v[192:195], v[116:119]
	v_mfma_i32_16x16x64_i8 v[112:115], v[152:155], v[192:195], v[112:115]
	v_mfma_i32_16x16x64_i8 v[104:107], v[144:147], v[200:203], v[104:107]
	v_mfma_i32_16x16x64_i8 v[96:99], v[152:155], v[200:203], v[96:99]
	v_mfma_i32_16x16x64_i8 v[88:91], v[144:147], v[208:211], v[88:91]
	v_mfma_i32_16x16x64_i8 v[80:83], v[152:155], v[208:211], v[80:83]
	s_setprio 0
	s_setprio 1
	v_mfma_i32_16x16x64_i8 v[108:111], v[156:159], v[180:183], v[108:111]
	v_mfma_i32_16x16x64_i8 v[100:103], v[164:167], v[180:183], v[100:103]
	v_mfma_i32_16x16x64_i8 v[92:95], v[156:159], v[188:191], v[92:95]
	v_mfma_i32_16x16x64_i8 v[84:87], v[164:167], v[188:191], v[84:87]
	v_mfma_i32_16x16x64_i8 v[76:79], v[156:159], v[196:199], v[76:79]
	v_mfma_i32_16x16x64_i8 v[72:75], v[164:167], v[196:199], v[72:75]
	v_mfma_i32_16x16x64_i8 v[68:71], v[156:159], v[204:207], v[68:71]
	v_mfma_i32_16x16x64_i8 v[64:67], v[164:167], v[204:207], v[64:67]
	v_mfma_i32_16x16x64_i8 v[108:111], v[160:163], v[184:187], v[108:111]
	v_mfma_i32_16x16x64_i8 v[100:103], v[168:171], v[184:187], v[100:103]
	v_mfma_i32_16x16x64_i8 v[92:95], v[160:163], v[192:195], v[92:95]
	v_mfma_i32_16x16x64_i8 v[84:87], v[168:171], v[192:195], v[84:87]
	v_mfma_i32_16x16x64_i8 v[76:79], v[160:163], v[200:203], v[76:79]
	v_mfma_i32_16x16x64_i8 v[72:75], v[168:171], v[200:203], v[72:75]
	v_mfma_i32_16x16x64_i8 v[68:71], v[160:163], v[208:211], v[68:71]
	v_mfma_i32_16x16x64_i8 v[64:67], v[168:171], v[208:211], v[64:67]
	s_setprio 0
	s_barrier
	s_add_u32 s98, s38, s20
	s_addc_u32 s99, s39, s21
	s_add_u32 s100, s40, s20
	s_addc_u32 s101, s41, s21
	s_sub_u32 s100, s100, 0x80000
	s_subb_u32 s101, s101, 0
	s_add_i32 s40, s75, s42
	s_mov_b32 m0, s40
	ds_read_b128 v[180:183], v178 offset:49152
	ds_read_b128 v[184:187], v178 offset:50176
	ds_read_b128 v[188:191], v178 offset:51200
	ds_read_b128 v[192:195], v178 offset:52224
	global_load_lds_dwordx4 v130, s[98:99]
	s_add_i32 m0, s40, 0x2000
	s_add_u32 s38, s38, 0x80080
	s_addc_u32 s39, s39, 0
	s_add_i32 s40, s76, s42
	global_load_lds_dwordx4 v134, s[98:99]
	s_mov_b32 m0, s40
	ds_read_b128 v[208:211], v178 offset:56320
	global_load_lds_dwordx4 v130, s[38:39]
	s_add_i32 m0, s40, 0x2000
	ds_read_b128 v[204:207], v178 offset:55296
	global_load_lds_dwordx4 v134, s[38:39]
	s_mov_b32 m0, s51
	ds_read_b128 v[200:203], v178 offset:54272
	global_load_lds_dwordx4 v128, s[100:101]
	s_mov_b32 m0, s52
	ds_read_b128 v[196:199], v178 offset:53248
	global_load_lds_dwordx4 v132, s[100:101]
	s_waitcnt vmcnt(8)
	s_waitcnt lgkmcnt(0)
	s_barrier
	s_setprio 1
	s_waitcnt lgkmcnt(0)
	v_mfma_i32_16x16x64_i8 v[60:63], v[140:143], v[180:183], v[60:63]
	v_mfma_i32_16x16x64_i8 v[56:59], v[148:151], v[180:183], v[56:59]
	v_mfma_i32_16x16x64_i8 v[52:55], v[140:143], v[188:191], v[52:55]
	v_mfma_i32_16x16x64_i8 v[48:51], v[148:151], v[188:191], v[48:51]
	v_mfma_i32_16x16x64_i8 v[40:43], v[140:143], v[196:199], v[40:43]
	v_mfma_i32_16x16x64_i8 v[32:35], v[148:151], v[196:199], v[32:35]
	v_mfma_i32_16x16x64_i8 v[24:27], v[140:143], v[204:207], v[24:27]
	v_mfma_i32_16x16x64_i8 v[16:19], v[148:151], v[204:207], v[16:19]
	v_mfma_i32_16x16x64_i8 v[60:63], v[144:147], v[184:187], v[60:63]
	v_mfma_i32_16x16x64_i8 v[56:59], v[152:155], v[184:187], v[56:59]
	v_mfma_i32_16x16x64_i8 v[52:55], v[144:147], v[192:195], v[52:55]
	v_mfma_i32_16x16x64_i8 v[48:51], v[152:155], v[192:195], v[48:51]
	v_mfma_i32_16x16x64_i8 v[40:43], v[144:147], v[200:203], v[40:43]
	v_mfma_i32_16x16x64_i8 v[32:35], v[152:155], v[200:203], v[32:35]
	v_mfma_i32_16x16x64_i8 v[24:27], v[144:147], v[208:211], v[24:27]
	v_mfma_i32_16x16x64_i8 v[16:19], v[152:155], v[208:211], v[16:19]
	s_setprio 0
	s_setprio 1
	v_mfma_i32_16x16x64_i8 v[44:47], v[156:159], v[180:183], v[44:47]
	v_mfma_i32_16x16x64_i8 v[36:39], v[164:167], v[180:183], v[36:39]
	v_mfma_i32_16x16x64_i8 v[28:31], v[156:159], v[188:191], v[28:31]
	v_mfma_i32_16x16x64_i8 v[20:23], v[164:167], v[188:191], v[20:23]
	v_mfma_i32_16x16x64_i8 v[12:15], v[156:159], v[196:199], v[12:15]
	v_mfma_i32_16x16x64_i8 v[8:11], v[164:167], v[196:199], v[8:11]
	v_mfma_i32_16x16x64_i8 v[4:7], v[156:159], v[204:207], v[4:7]
	v_mfma_i32_16x16x64_i8 v[0:3], v[164:167], v[204:207], v[0:3]
	v_mfma_i32_16x16x64_i8 v[44:47], v[160:163], v[184:187], v[44:47]
	v_mfma_i32_16x16x64_i8 v[36:39], v[168:171], v[184:187], v[36:39]
	v_mfma_i32_16x16x64_i8 v[28:31], v[160:163], v[192:195], v[28:31]
	v_mfma_i32_16x16x64_i8 v[20:23], v[168:171], v[192:195], v[20:23]
	v_mfma_i32_16x16x64_i8 v[12:15], v[160:163], v[200:203], v[12:15]
	v_mfma_i32_16x16x64_i8 v[8:11], v[168:171], v[200:203], v[8:11]
	v_mfma_i32_16x16x64_i8 v[4:7], v[160:163], v[208:211], v[4:7]
	v_mfma_i32_16x16x64_i8 v[0:3], v[168:171], v[208:211], v[0:3]
	s_setprio 0
	s_barrier
	s_add_u32 s36, s36, 0x100
	s_addc_u32 s37, s37, 0
	s_add_u32 s72, s72, 0x100
	s_addc_u32 s73, s73, 0
	s_cmp_ge_i32 s74, s8
	s_mov_b32 s38, s74
	s_cbranch_scc0 .LBB0_1238

.Lq_body_L:
	s_add_i32 s74, s38, 2
	s_add_u32 s39, s36, 0xfff80080
	s_addc_u32 s40, s37, -1
	s_cmp_eq_u32 s71, s38
	s_cselect_b32 s41, s67, s40
	s_cselect_b32 s40, s68, s39
	ds_read_b128 v[140:143], v177
	ds_read_b128 v[144:147], v177 offset:1024
	ds_read_b128 v[148:151], v177 offset:2048
	ds_read_b128 v[152:155], v177 offset:3072
	ds_read_b128 v[156:159], v177 offset:16384
	ds_read_b128 v[160:163], v177 offset:17408
	ds_read_b128 v[164:167], v177 offset:18432
	ds_read_b128 v[168:171], v177 offset:19456
	s_cselect_b32 s38, s70, s72
	s_cselect_b32 s39, s69, s73
	s_add_i32 m0, s45, 0xc000
	ds_read_b128 v[180:183], v178
	ds_read_b128 v[184:187], v178 offset:1024
	ds_read_b128 v[188:191], v178 offset:2048
	ds_read_b128 v[192:195], v178 offset:3072
	ds_read_b128 v[196:199], v178 offset:4096
	ds_read_b128 v[200:203], v178 offset:5120
	ds_read_b128 v[204:207], v178 offset:6144
	global_load_lds_dwordx4 v136, s[36:37]
	s_add_i32 m0, s45, 0xe000
	ds_read_b128 v[208:211], v178 offset:7168
	global_load_lds_dwordx4 v138, s[36:37]
	global_load_dwordx4 v[226:229], v223, s[100:101] nt
	s_add_u32 s84, s84, 1
	s_waitcnt vmcnt(9)
	s_waitcnt lgkmcnt(0)
	s_barrier
	s_setprio 1
	s_waitcnt lgkmcnt(0)
	v_mfma_i32_16x16x64_i8 v[124:127], v[140:143], v[180:183], v[124:127]
	v_mfma_i32_16x16x64_i8 v[120:123], v[148:151], v[180:183], v[120:123]
	v_mfma_i32_16x16x64_i8 v[116:119], v[140:143], v[188:191], v[116:119]
	v_mfma_i32_16x16x64_i8 v[112:115], v[148:151], v[188:191], v[112:115]
	v_mfma_i32_16x16x64_i8 v[104:107], v[140:143], v[196:199], v[104:107]
	v_mfma_i32_16x16x64_i8 v[96:99], v[148:151], v[196:199], v[96:99]
	v_mfma_i32_16x16x64_i8 v[88:91], v[140:143], v[204:207], v[88:91]
	v_mfma_i32_16x16x64_i8 v[80:83], v[148:151], v[204:207], v[80:83]
	v_mfma_i32_16x16x64_i8 v[124:127], v[144:147], v[184:187], v[124:127]
	v_mfma_i32_16x16x64_i8 v[120:123], v[152:155], v[184:187], v[120:123]
	v_mfma_i32_16x16x64_i8 v[116:119], v[144:147], v[192:195], v[116:119]
	v_mfma_i32_16x16x64_i8 v[112:115], v[152:155], v[192:195], v[112:115]
	v_mfma_i32_16x16x64_i8 v[104:107], v[144:147], v[200:203], v[104:107]
	v_mfma_i32_16x16x64_i8 v[96:99], v[152:155], v[200:203], v[96:99]
	v_mfma_i32_16x16x64_i8 v[88:91], v[144:147], v[208:211], v[88:91]
	v_mfma_i32_16x16x64_i8 v[80:83], v[152:155], v[208:211], v[80:83]
	s_setprio 0
	s_setprio 1
	v_mfma_i32_16x16x64_i8 v[108:111], v[156:159], v[180:183], v[108:111]
	v_mfma_i32_16x16x64_i8 v[100:103], v[164:167], v[180:183], v[100:103]
	v_mfma_i32_16x16x64_i8 v[92:95], v[156:159], v[188:191], v[92:95]
	v_mfma_i32_16x16x64_i8 v[84:87], v[164:167], v[188:191], v[84:87]
	v_mfma_i32_16x16x64_i8 v[76:79], v[156:159], v[196:199], v[76:79]
	v_mfma_i32_16x16x64_i8 v[72:75], v[164:167], v[196:199], v[72:75]
	v_mfma_i32_16x16x64_i8 v[68:71], v[156:159], v[204:207], v[68:71]
	v_mfma_i32_16x16x64_i8 v[64:67], v[164:167], v[204:207], v[64:67]
	v_mfma_i32_16x16x64_i8 v[108:111], v[160:163], v[184:187], v[108:111]
	v_mfma_i32_16x16x64_i8 v[100:103], v[168:171], v[184:187], v[100:103]
	v_mfma_i32_16x16x64_i8 v[92:95], v[160:163], v[192:195], v[92:95]
	v_mfma_i32_16x16x64_i8 v[84:87], v[168:171], v[192:195], v[84:87]
	v_mfma_i32_16x16x64_i8 v[76:79], v[160:163], v[200:203], v[76:79]
	v_mfma_i32_16x16x64_i8 v[72:75], v[168:171], v[200:203], v[72:75]
	v_mfma_i32_16x16x64_i8 v[68:71], v[160:163], v[208:211], v[68:71]
	v_mfma_i32_16x16x64_i8 v[64:67], v[168:171], v[208:211], v[64:67]
	s_setprio 0
	s_barrier
	s_add_i32 s75, s55, s42
	v_lshl_add_u64 v[172:173], s[38:39], 0, v[130:131]
	s_mov_b32 m0, s75
	ds_read_b128 v[180:183], v178 offset:16384
	ds_read_b128 v[184:187], v178 offset:17408
	ds_read_b128 v[188:191], v178 offset:18432
	ds_read_b128 v[192:195], v178 offset:19456
	ds_read_b128 v[196:199], v178 offset:20480
	global_load_lds_dwordx4 v130, s[38:39]
	s_add_i32 m0, s75, 0x2000
	s_add_u32 s76, s38, 0x80000
	v_lshl_add_u64 v[212:213], s[38:39], 0, v[134:135]
	s_addc_u32 s77, s39, 0
	s_add_i32 s75, s60, s42
	global_load_lds_dwordx4 v134, s[38:39]
	s_mov_b32 m0, s75
	v_lshl_add_u64 v[216:217], s[40:41], 0, v[132:133]
	global_load_lds_dwordx4 v130, s[76:77]
	s_add_i32 m0, s75, 0x2000
	ds_read_b128 v[208:211], v178 offset:23552
	global_load_lds_dwordx4 v134, s[76:77]
	v_lshl_add_u64 v[214:215], s[40:41], 0, v[128:129]
	s_mov_b32 m0, s45
	ds_read_b128 v[204:207], v178 offset:22528
	global_load_lds_dwordx4 v128, s[40:41]
	s_mov_b32 m0, s46
	ds_read_b128 v[200:203], v178 offset:21504
	global_load_lds_dwordx4 v132, s[40:41]
	s_waitcnt vmcnt(9)
	s_waitcnt lgkmcnt(0)
	s_barrier
	s_setprio 1
	s_waitcnt lgkmcnt(0)
	v_mfma_i32_16x16x64_i8 v[60:63], v[140:143], v[180:183], v[60:63]
	v_mfma_i32_16x16x64_i8 v[56:59], v[148:151], v[180:183], v[56:59]
	v_mfma_i32_16x16x64_i8 v[52:55], v[140:143], v[188:191], v[52:55]
	v_mfma_i32_16x16x64_i8 v[48:51], v[148:151], v[188:191], v[48:51]
	v_mfma_i32_16x16x64_i8 v[40:43], v[140:143], v[196:199], v[40:43]
	v_mfma_i32_16x16x64_i8 v[32:35], v[148:151], v[196:199], v[32:35]
	v_mfma_i32_16x16x64_i8 v[24:27], v[140:143], v[204:207], v[24:27]
	v_mfma_i32_16x16x64_i8 v[16:19], v[148:151], v[204:207], v[16:19]
	v_mfma_i32_16x16x64_i8 v[60:63], v[144:147], v[184:187], v[60:63]
	v_mfma_i32_16x16x64_i8 v[56:59], v[152:155], v[184:187], v[56:59]
	v_mfma_i32_16x16x64_i8 v[52:55], v[144:147], v[192:195], v[52:55]
	v_mfma_i32_16x16x64_i8 v[48:51], v[152:155], v[192:195], v[48:51]
	v_mfma_i32_16x16x64_i8 v[40:43], v[144:147], v[200:203], v[40:43]
	v_mfma_i32_16x16x64_i8 v[32:35], v[152:155], v[200:203], v[32:35]
	v_mfma_i32_16x16x64_i8 v[24:27], v[144:147], v[208:211], v[24:27]
	v_mfma_i32_16x16x64_i8 v[16:19], v[152:155], v[208:211], v[16:19]
	s_setprio 0
	s_setprio 1
	v_mfma_i32_16x16x64_i8 v[44:47], v[156:159], v[180:183], v[44:47]
	v_mfma_i32_16x16x64_i8 v[36:39], v[164:167], v[180:183], v[36:39]
	v_mfma_i32_16x16x64_i8 v[28:31], v[156:159], v[188:191], v[28:31]
	v_mfma_i32_16x16x64_i8 v[20:23], v[164:167], v[188:191], v[20:23]
	v_mfma_i32_16x16x64_i8 v[12:15], v[156:159], v[196:199], v[12:15]
	v_mfma_i32_16x16x64_i8 v[8:11], v[164:167], v[196:199], v[8:11]
	v_mfma_i32_16x16x64_i8 v[4:7], v[156:159], v[204:207], v[4:7]
	v_mfma_i32_16x16x64_i8 v[0:3], v[164:167], v[204:207], v[0:3]
	v_mfma_i32_16x16x64_i8 v[44:47], v[160:163], v[184:187], v[44:47]
	v_mfma_i32_16x16x64_i8 v[36:39], v[168:171], v[184:187], v[36:39]
	v_mfma_i32_16x16x64_i8 v[28:31], v[160:163], v[192:195], v[28:31]
	v_mfma_i32_16x16x64_i8 v[20:23], v[168:171], v[192:195], v[20:23]
	v_mfma_i32_16x16x64_i8 v[12:15], v[160:163], v[200:203], v[12:15]
	v_mfma_i32_16x16x64_i8 v[8:11], v[168:171], v[200:203], v[8:11]
	v_mfma_i32_16x16x64_i8 v[4:7], v[160:163], v[208:211], v[4:7]
	v_mfma_i32_16x16x64_i8 v[0:3], v[168:171], v[208:211], v[0:3]
	s_setprio 0
	s_barrier
	s_add_i32 s75, 0, 0x18000
	s_add_i32 s76, 0, 0x1c000
	ds_read_b128 v[140:143], v177 offset:32768
	ds_read_b128 v[144:147], v177 offset:33792
	ds_read_b128 v[148:151], v177 offset:34816
	ds_read_b128 v[152:155], v177 offset:35840
	ds_read_b128 v[156:159], v177 offset:49152
	ds_read_b128 v[160:163], v177 offset:50176
	ds_read_b128 v[164:167], v177 offset:51200
	ds_read_b128 v[168:171], v177 offset:52224
	s_add_u32 s40, s40, 0x80000
	s_addc_u32 s41, s41, 0
	s_mov_b32 m0, s47
	ds_read_b128 v[180:183], v178 offset:32768
	ds_read_b128 v[184:187], v178 offset:33792
	ds_read_b128 v[188:191], v178 offset:34816
	ds_read_b128 v[192:195], v178 offset:35840
	ds_read_b128 v[196:199], v178 offset:36864
	ds_read_b128 v[200:203], v178 offset:37888
	ds_read_b128 v[204:207], v178 offset:38912
	global_load_lds_dwordx4 v128, s[40:41]
	s_mov_b32 m0, s48
	ds_read_b128 v[208:211], v178 offset:39936
	global_load_lds_dwordx4 v132, s[40:41]
	s_waitcnt vmcnt(9)
	s_waitcnt lgkmcnt(0)
	s_barrier
	s_setprio 1
	s_waitcnt lgkmcnt(0)
	v_mfma_i32_16x16x64_i8 v[124:127], v[140:143], v[180:183], v[124:127]
	v_mfma_i32_16x16x64_i8 v[120:123], v[148:151], v[180:183], v[120:123]
	v_mfma_i32_16x16x64_i8 v[116:119], v[140:143], v[188:191], v[116:119]
	v_mfma_i32_16x16x64_i8 v[112:115], v[148:151], v[188:191], v[112:115]
	v_mfma_i32_16x16x64_i8 v[104:107], v[140:143], v[196:199], v[104:107]
	v_mfma_i32_16x16x64_i8 v[96:99], v[148:151], v[196:199], v[96:99]
	v_mfma_i32_16x16x64_i8 v[88:91], v[140:143], v[204:207], v[88:91]
	v_mfma_i32_16x16x64_i8 v[80:83], v[148:151], v[204:207], v[80:83]
	v_mfma_i32_16x16x64_i8 v[124:127], v[144:147], v[184:187], v[124:127]
	v_mfma_i32_16x16x64_i8 v[120:123], v[152:155], v[184:187], v[120:123]
	v_mfma_i32_16x16x64_i8 v[116:119], v[144:147], v[192:195], v[116:119]
	v_mfma_i32_16x16x64_i8 v[112:115], v[152:155], v[192:195], v[112:115]
	v_mfma_i32_16x16x64_i8 v[104:107], v[144:147], v[200:203], v[104:107]
	v_mfma_i32_16x16x64_i8 v[96:99], v[152:155], v[200:203], v[96:99]
	v_mfma_i32_16x16x64_i8 v[88:91], v[144:147], v[208:211], v[88:91]
	v_mfma_i32_16x16x64_i8 v[80:83], v[152:155], v[208:211], v[80:83]
	s_setprio 0
	s_setprio 1
	v_mfma_i32_16x16x64_i8 v[108:111], v[156:159], v[180:183], v[108:111]
	v_mfma_i32_16x16x64_i8 v[100:103], v[164:167], v[180:183], v[100:103]
	v_mfma_i32_16x16x64_i8 v[92:95], v[156:159], v[188:191], v[92:95]
	v_mfma_i32_16x16x64_i8 v[84:87], v[164:167], v[188:191], v[84:87]
	v_mfma_i32_16x16x64_i8 v[76:79], v[156:159], v[196:199], v[76:79]
	v_mfma_i32_16x16x64_i8 v[72:75], v[164:167], v[196:199], v[72:75]
	v_mfma_i32_16x16x64_i8 v[68:71], v[156:159], v[204:207], v[68:71]
	v_mfma_i32_16x16x64_i8 v[64:67], v[164:167], v[204:207], v[64:67]
	v_mfma_i32_16x16x64_i8 v[108:111], v[160:163], v[184:187], v[108:111]
	v_mfma_i32_16x16x64_i8 v[100:103], v[168:171], v[184:187], v[100:103]
	v_mfma_i32_16x16x64_i8 v[92:95], v[160:163], v[192:195], v[92:95]
	v_mfma_i32_16x16x64_i8 v[84:87], v[168:171], v[192:195], v[84:87]
	v_mfma_i32_16x16x64_i8 v[76:79], v[160:163], v[200:203], v[76:79]
	v_mfma_i32_16x16x64_i8 v[72:75], v[168:171], v[200:203], v[72:75]
	v_mfma_i32_16x16x64_i8 v[68:71], v[160:163], v[208:211], v[68:71]
	v_mfma_i32_16x16x64_i8 v[64:67], v[168:171], v[208:211], v[64:67]
	s_setprio 0
	s_barrier
	s_add_i32 s40, s75, s42
	v_lshl_add_u64 v[172:173], v[172:173], 0, s[20:21]
	s_mov_b32 m0, s40
	ds_read_b128 v[180:183], v178 offset:49152
	ds_read_b128 v[184:187], v178 offset:50176
	ds_read_b128 v[188:191], v178 offset:51200
	ds_read_b128 v[192:195], v178 offset:52224
	global_load_lds_dwordx4 v[172:173], off
	s_add_i32 m0, s40, 0x2000
	s_add_u32 s38, s38, 0x80080
	v_lshl_add_u64 v[172:173], v[212:213], 0, s[20:21]
	s_addc_u32 s39, s39, 0
	s_add_i32 s40, s76, s42
	global_load_lds_dwordx4 v[172:173], off
	s_mov_b32 m0, s40
	ds_read_b128 v[208:211], v178 offset:56320
	global_load_lds_dwordx4 v130, s[38:39]
	s_add_i32 m0, s40, 0x2000
	ds_read_b128 v[204:207], v178 offset:55296
	global_load_lds_dwordx4 v134, s[38:39]
	v_lshl_add_u64 v[172:173], v[214:215], 0, s[20:21]
	s_mov_b32 m0, s51
	ds_read_b128 v[200:203], v178 offset:54272
	global_load_lds_dwordx4 v[172:173], off
	v_lshl_add_u64 v[172:173], v[216:217], 0, s[20:21]
	s_mov_b32 m0, s52
	ds_read_b128 v[196:199], v178 offset:53248
	global_load_lds_dwordx4 v[172:173], off
	s_waitcnt vmcnt(8)
	s_waitcnt lgkmcnt(0)
	s_barrier
	s_setprio 1
	s_waitcnt lgkmcnt(0)
	v_mfma_i32_16x16x64_i8 v[60:63], v[140:143], v[180:183], v[60:63]
	v_mfma_i32_16x16x64_i8 v[56:59], v[148:151], v[180:183], v[56:59]
	v_mfma_i32_16x16x64_i8 v[52:55], v[140:143], v[188:191], v[52:55]
	v_fmaak_f32 v226, v226, v220, 0x4b400000
	v_mfma_i32_16x16x64_i8 v[48:51], v[148:151], v[188:191], v[48:51]
	v_mfma_i32_16x16x64_i8 v[40:43], v[140:143], v[196:199], v[40:43]
	v_mfma_i32_16x16x64_i8 v[32:35], v[148:151], v[196:199], v[32:35]
	v_fmaak_f32 v227, v227, v225, 0x4b400000
	v_mfma_i32_16x16x64_i8 v[24:27], v[140:143], v[204:207], v[24:27]
	v_mfma_i32_16x16x64_i8 v[16:19], v[148:151], v[204:207], v[16:19]
	v_mfma_i32_16x16x64_i8 v[60:63], v[144:147], v[184:187], v[60:63]
	v_fmaak_f32 v228, v228, v252, 0x4b400000
	v_mfma_i32_16x16x64_i8 v[56:59], v[152:155], v[184:187], v[56:59]
	v_mfma_i32_16x16x64_i8 v[52:55], v[144:147], v[192:195], v[52:55]
	v_mfma_i32_16x16x64_i8 v[48:51], v[152:155], v[192:195], v[48:51]
	v_fmaak_f32 v229, v229, v253, 0x4b400000
	v_mfma_i32_16x16x64_i8 v[40:43], v[144:147], v[200:203], v[40:43]
	v_mfma_i32_16x16x64_i8 v[32:35], v[152:155], v[200:203], v[32:35]
	v_mfma_i32_16x16x64_i8 v[24:27], v[144:147], v[208:211], v[24:27]
	v_alignbit_b32 v239, v226, v239, 8
	v_mfma_i32_16x16x64_i8 v[16:19], v[152:155], v[208:211], v[16:19]
	s_setprio 0
	s_setprio 1
	v_mfma_i32_16x16x64_i8 v[44:47], v[156:159], v[180:183], v[44:47]
	v_mfma_i32_16x16x64_i8 v[36:39], v[164:167], v[180:183], v[36:39]
	v_alignbit_b32 v243, v227, v243, 8
	v_mfma_i32_16x16x64_i8 v[28:31], v[156:159], v[188:191], v[28:31]
	v_mfma_i32_16x16x64_i8 v[20:23], v[164:167], v[188:191], v[20:23]
	v_mfma_i32_16x16x64_i8 v[12:15], v[156:159], v[196:199], v[12:15]
	v_alignbit_b32 v247, v228, v247, 8
	v_mfma_i32_16x16x64_i8 v[8:11], v[164:167], v[196:199], v[8:11]
	v_mfma_i32_16x16x64_i8 v[4:7], v[156:159], v[204:207], v[4:7]
	v_mfma_i32_16x16x64_i8 v[0:3], v[164:167], v[204:207], v[0:3]
	v_alignbit_b32 v251, v229, v251, 8
	v_mfma_i32_16x16x64_i8 v[44:47], v[160:163], v[184:187], v[44:47]
	v_mfma_i32_16x16x64_i8 v[36:39], v[168:171], v[184:187], v[36:39]
	v_mfma_i32_16x16x64_i8 v[28:31], v[160:163], v[192:195], v[28:31]
	v_add_u32_e32 v223, 0x4000, v223
	v_mfma_i32_16x16x64_i8 v[20:23], v[168:171], v[192:195], v[20:23]
	v_mfma_i32_16x16x64_i8 v[12:15], v[160:163], v[200:203], v[12:15]
	v_mfma_i32_16x16x64_i8 v[8:11], v[168:171], v[200:203], v[8:11]
	v_mfma_i32_16x16x64_i8 v[4:7], v[160:163], v[208:211], v[4:7]
	v_mfma_i32_16x16x64_i8 v[0:3], v[168:171], v[208:211], v[0:3]
	s_setprio 0
	s_barrier
	s_and_b32 s77, s84, 3
	s_cbranch_scc0 .Lq_mv_L

.Lq_body_ST:
	s_add_i32 s74, s38, 2
	s_add_u32 s39, s36, 0xfff80080
	s_addc_u32 s40, s37, -1
	s_cmp_eq_u32 s71, s38
	s_cselect_b32 s41, s67, s40
	s_cselect_b32 s40, s68, s39
	ds_read_b128 v[140:143], v177
	ds_read_b128 v[144:147], v177 offset:1024
	ds_read_b128 v[148:151], v177 offset:2048
	ds_read_b128 v[152:155], v177 offset:3072
	ds_read_b128 v[156:159], v177 offset:16384
	ds_read_b128 v[160:163], v177 offset:17408
	ds_read_b128 v[164:167], v177 offset:18432
	ds_read_b128 v[168:171], v177 offset:19456
	s_cselect_b32 s38, s70, s72
	s_cselect_b32 s39, s69, s73
	s_add_i32 m0, s45, 0xc000
	ds_read_b128 v[180:183], v178
	ds_read_b128 v[184:187], v178 offset:1024
	ds_read_b128 v[188:191], v178 offset:2048
	ds_read_b128 v[192:195], v178 offset:3072
	ds_read_b128 v[196:199], v178 offset:4096
	ds_read_b128 v[200:203], v178 offset:5120
	ds_read_b128 v[204:207], v178 offset:6144
	global_load_lds_dwordx4 v136, s[36:37]
	s_add_i32 m0, s45, 0xe000
	ds_read_b128 v[208:211], v178 offset:7168
	global_load_lds_dwordx4 v138, s[36:37]
	global_store_dwordx4 v224, v[236:239], s[98:99]
	s_add_u32 s98, s98, 0x2b00
	s_addc_u32 s99, s99, 0
	global_store_dwordx4 v224, v[240:243], s[98:99]
	s_add_u32 s98, s98, 0x2b00
	s_addc_u32 s99, s99, 0
	global_store_dwordx4 v224, v[244:247], s[98:99]
	s_add_u32 s98, s98, 0x2b00
	s_addc_u32 s99, s99, 0
	global_store_dwordx4 v224, v[248:251], s[98:99]
	v_subrev_u32_e32 v223, 0x40000, v223
	s_cmp_lt_u32 s84, s87
	s_cbranch_scc0 .Lq_st_last
	s_cmp_lt_u32 s84, s89
	s_cbranch_scc0 .Lq_st_full
	s_sub_u32 s98, s98, 0x8080
	s_subb_u32 s99, s99, 0
	s_add_u32 s100, s100, 0x200000
	s_addc_u32 s101, s101, 0

.Lq_st_j:
	s_waitcnt vmcnt(13)
	s_waitcnt lgkmcnt(0)
	s_barrier
	s_setprio 1
	s_waitcnt lgkmcnt(0)
	v_mfma_i32_16x16x64_i8 v[124:127], v[140:143], v[180:183], v[124:127]
	v_mfma_i32_16x16x64_i8 v[120:123], v[148:151], v[180:183], v[120:123]
	v_mfma_i32_16x16x64_i8 v[116:119], v[140:143], v[188:191], v[116:119]
	v_mfma_i32_16x16x64_i8 v[112:115], v[148:151], v[188:191], v[112:115]
	v_mfma_i32_16x16x64_i8 v[104:107], v[140:143], v[196:199], v[104:107]
	v_mfma_i32_16x16x64_i8 v[96:99], v[148:151], v[196:199], v[96:99]
	v_mfma_i32_16x16x64_i8 v[88:91], v[140:143], v[204:207], v[88:91]
	v_mfma_i32_16x16x64_i8 v[80:83], v[148:151], v[204:207], v[80:83]
	v_mfma_i32_16x16x64_i8 v[124:127], v[144:147], v[184:187], v[124:127]
	v_mfma_i32_16x16x64_i8 v[120:123], v[152:155], v[184:187], v[120:123]
	v_mfma_i32_16x16x64_i8 v[116:119], v[144:147], v[192:195], v[116:119]
	v_mfma_i32_16x16x64_i8 v[112:115], v[152:155], v[192:195], v[112:115]
	v_mfma_i32_16x16x64_i8 v[104:107], v[144:147], v[200:203], v[104:107]
	v_mfma_i32_16x16x64_i8 v[96:99], v[152:155], v[200:203], v[96:99]
	v_mfma_i32_16x16x64_i8 v[88:91], v[144:147], v[208:211], v[88:91]
	v_mfma_i32_16x16x64_i8 v[80:83], v[152:155], v[208:211], v[80:83]
	s_setprio 0
	s_setprio 1
	v_mfma_i32_16x16x64_i8 v[108:111], v[156:159], v[180:183], v[108:111]
	v_mfma_i32_16x16x64_i8 v[100:103], v[164:167], v[180:183], v[100:103]
	v_mfma_i32_16x16x64_i8 v[92:95], v[156:159], v[188:191], v[92:95]
	v_mfma_i32_16x16x64_i8 v[84:87], v[164:167], v[188:191], v[84:87]
	v_mfma_i32_16x16x64_i8 v[76:79], v[156:159], v[196:199], v[76:79]
	v_mfma_i32_16x16x64_i8 v[72:75], v[164:167], v[196:199], v[72:75]
	v_mfma_i32_16x16x64_i8 v[68:71], v[156:159], v[204:207], v[68:71]
	v_mfma_i32_16x16x64_i8 v[64:67], v[164:167], v[204:207], v[64:67]
	v_mfma_i32_16x16x64_i8 v[108:111], v[160:163], v[184:187], v[108:111]
	v_mfma_i32_16x16x64_i8 v[100:103], v[168:171], v[184:187], v[100:103]
	v_mfma_i32_16x16x64_i8 v[92:95], v[160:163], v[192:195], v[92:95]
	v_mfma_i32_16x16x64_i8 v[84:87], v[168:171], v[192:195], v[84:87]
	v_mfma_i32_16x16x64_i8 v[76:79], v[160:163], v[200:203], v[76:79]
	v_mfma_i32_16x16x64_i8 v[72:75], v[168:171], v[200:203], v[72:75]
	v_mfma_i32_16x16x64_i8 v[68:71], v[160:163], v[208:211], v[68:71]
	v_mfma_i32_16x16x64_i8 v[64:67], v[168:171], v[208:211], v[64:67]
	s_setprio 0
	s_barrier
	s_add_i32 s75, s55, s42
	v_lshl_add_u64 v[172:173], s[38:39], 0, v[130:131]
	s_mov_b32 m0, s75
	ds_read_b128 v[180:183], v178 offset:16384
	ds_read_b128 v[184:187], v178 offset:17408
	ds_read_b128 v[188:191], v178 offset:18432
	ds_read_b128 v[192:195], v178 offset:19456
	ds_read_b128 v[196:199], v178 offset:20480
	global_load_lds_dwordx4 v130, s[38:39]
	s_add_i32 m0, s75, 0x2000
	s_add_u32 s76, s38, 0x80000
	v_lshl_add_u64 v[212:213], s[38:39], 0, v[134:135]
	s_addc_u32 s77, s39, 0
	s_add_i32 s75, s60, s42
	global_load_lds_dwordx4 v134, s[38:39]
	s_mov_b32 m0, s75
	v_lshl_add_u64 v[216:217], s[40:41], 0, v[132:133]
	global_load_lds_dwordx4 v130, s[76:77]
	s_add_i32 m0, s75, 0x2000
	ds_read_b128 v[208:211], v178 offset:23552
	global_load_lds_dwordx4 v134, s[76:77]
	v_lshl_add_u64 v[214:215], s[40:41], 0, v[128:129]
	s_mov_b32 m0, s45
	ds_read_b128 v[204:207], v178 offset:22528
	global_load_lds_dwordx4 v128, s[40:41]
	s_mov_b32 m0, s46
	ds_read_b128 v[200:203], v178 offset:21504
	global_load_lds_dwordx4 v132, s[40:41]
	s_waitcnt vmcnt(13)
	s_waitcnt lgkmcnt(0)
	s_barrier
	s_setprio 1
	s_waitcnt lgkmcnt(0)
	v_mfma_i32_16x16x64_i8 v[60:63], v[140:143], v[180:183], v[60:63]
	v_mfma_i32_16x16x64_i8 v[56:59], v[148:151], v[180:183], v[56:59]
	v_mfma_i32_16x16x64_i8 v[52:55], v[140:143], v[188:191], v[52:55]
	v_mfma_i32_16x16x64_i8 v[48:51], v[148:151], v[188:191], v[48:51]
	v_mfma_i32_16x16x64_i8 v[40:43], v[140:143], v[196:199], v[40:43]
	v_mfma_i32_16x16x64_i8 v[32:35], v[148:151], v[196:199], v[32:35]
	v_mfma_i32_16x16x64_i8 v[24:27], v[140:143], v[204:207], v[24:27]
	v_mfma_i32_16x16x64_i8 v[16:19], v[148:151], v[204:207], v[16:19]
	v_mfma_i32_16x16x64_i8 v[60:63], v[144:147], v[184:187], v[60:63]
	v_mfma_i32_16x16x64_i8 v[56:59], v[152:155], v[184:187], v[56:59]
	v_mfma_i32_16x16x64_i8 v[52:55], v[144:147], v[192:195], v[52:55]
	v_mfma_i32_16x16x64_i8 v[48:51], v[152:155], v[192:195], v[48:51]
	v_mfma_i32_16x16x64_i8 v[40:43], v[144:147], v[200:203], v[40:43]
	v_mfma_i32_16x16x64_i8 v[32:35], v[152:155], v[200:203], v[32:35]
	v_mfma_i32_16x16x64_i8 v[24:27], v[144:147], v[208:211], v[24:27]
	v_mfma_i32_16x16x64_i8 v[16:19], v[152:155], v[208:211], v[16:19]
	s_setprio 0
	s_setprio 1
	v_mfma_i32_16x16x64_i8 v[44:47], v[156:159], v[180:183], v[44:47]
	v_mfma_i32_16x16x64_i8 v[36:39], v[164:167], v[180:183], v[36:39]
	v_mfma_i32_16x16x64_i8 v[28:31], v[156:159], v[188:191], v[28:31]
	v_mfma_i32_16x16x64_i8 v[20:23], v[164:167], v[188:191], v[20:23]
	v_mfma_i32_16x16x64_i8 v[12:15], v[156:159], v[196:199], v[12:15]
	v_mfma_i32_16x16x64_i8 v[8:11], v[164:167], v[196:199], v[8:11]
	v_mfma_i32_16x16x64_i8 v[4:7], v[156:159], v[204:207], v[4:7]
	v_mfma_i32_16x16x64_i8 v[0:3], v[164:167], v[204:207], v[0:3]
	v_mfma_i32_16x16x64_i8 v[44:47], v[160:163], v[184:187], v[44:47]
	v_mfma_i32_16x16x64_i8 v[36:39], v[168:171], v[184:187], v[36:39]
	v_mfma_i32_16x16x64_i8 v[28:31], v[160:163], v[192:195], v[28:31]
	v_mfma_i32_16x16x64_i8 v[20:23], v[168:171], v[192:195], v[20:23]
	v_mfma_i32_16x16x64_i8 v[12:15], v[160:163], v[200:203], v[12:15]
	v_mfma_i32_16x16x64_i8 v[8:11], v[168:171], v[200:203], v[8:11]
	v_mfma_i32_16x16x64_i8 v[4:7], v[160:163], v[208:211], v[4:7]
	v_mfma_i32_16x16x64_i8 v[0:3], v[168:171], v[208:211], v[0:3]
	s_setprio 0
	s_barrier
	s_add_i32 s75, 0, 0x18000
	s_add_i32 s76, 0, 0x1c000
	ds_read_b128 v[140:143], v177 offset:32768
	ds_read_b128 v[144:147], v177 offset:33792
	ds_read_b128 v[148:151], v177 offset:34816
	ds_read_b128 v[152:155], v177 offset:35840
	ds_read_b128 v[156:159], v177 offset:49152
	ds_read_b128 v[160:163], v177 offset:50176
	ds_read_b128 v[164:167], v177 offset:51200
	ds_read_b128 v[168:171], v177 offset:52224
	s_add_u32 s40, s40, 0x80000
	s_addc_u32 s41, s41, 0
	s_mov_b32 m0, s47
	ds_read_b128 v[180:183], v178 offset:32768
	ds_read_b128 v[184:187], v178 offset:33792
	ds_read_b128 v[188:191], v178 offset:34816
	ds_read_b128 v[192:195], v178 offset:35840
	ds_read_b128 v[196:199], v178 offset:36864
	ds_read_b128 v[200:203], v178 offset:37888
	ds_read_b128 v[204:207], v178 offset:38912
	global_load_lds_dwordx4 v128, s[40:41]
	s_mov_b32 m0, s48
	ds_read_b128 v[208:211], v178 offset:39936
	global_load_lds_dwordx4 v132, s[40:41]
	s_waitcnt vmcnt(13)
	s_waitcnt lgkmcnt(0)
	s_barrier
	s_setprio 1
	s_waitcnt lgkmcnt(0)
	v_mfma_i32_16x16x64_i8 v[124:127], v[140:143], v[180:183], v[124:127]
	v_mfma_i32_16x16x64_i8 v[120:123], v[148:151], v[180:183], v[120:123]
	v_mfma_i32_16x16x64_i8 v[116:119], v[140:143], v[188:191], v[116:119]
	v_mfma_i32_16x16x64_i8 v[112:115], v[148:151], v[188:191], v[112:115]
	v_mfma_i32_16x16x64_i8 v[104:107], v[140:143], v[196:199], v[104:107]
	v_mfma_i32_16x16x64_i8 v[96:99], v[148:151], v[196:199], v[96:99]
	v_mfma_i32_16x16x64_i8 v[88:91], v[140:143], v[204:207], v[88:91]
	v_mfma_i32_16x16x64_i8 v[80:83], v[148:151], v[204:207], v[80:83]
	v_mfma_i32_16x16x64_i8 v[124:127], v[144:147], v[184:187], v[124:127]
	v_mfma_i32_16x16x64_i8 v[120:123], v[152:155], v[184:187], v[120:123]
	v_mfma_i32_16x16x64_i8 v[116:119], v[144:147], v[192:195], v[116:119]
	v_mfma_i32_16x16x64_i8 v[112:115], v[152:155], v[192:195], v[112:115]
	v_mfma_i32_16x16x64_i8 v[104:107], v[144:147], v[200:203], v[104:107]
	v_mfma_i32_16x16x64_i8 v[96:99], v[152:155], v[200:203], v[96:99]
	v_mfma_i32_16x16x64_i8 v[88:91], v[144:147], v[208:211], v[88:91]
	v_mfma_i32_16x16x64_i8 v[80:83], v[152:155], v[208:211], v[80:83]
	s_setprio 0
	s_setprio 1
	v_mfma_i32_16x16x64_i8 v[108:111], v[156:159], v[180:183], v[108:111]
	v_mfma_i32_16x16x64_i8 v[100:103], v[164:167], v[180:183], v[100:103]
	v_mfma_i32_16x16x64_i8 v[92:95], v[156:159], v[188:191], v[92:95]
	v_mfma_i32_16x16x64_i8 v[84:87], v[164:167], v[188:191], v[84:87]
	v_mfma_i32_16x16x64_i8 v[76:79], v[156:159], v[196:199], v[76:79]
	v_mfma_i32_16x16x64_i8 v[72:75], v[164:167], v[196:199], v[72:75]
	v_mfma_i32_16x16x64_i8 v[68:71], v[156:159], v[204:207], v[68:71]
	v_mfma_i32_16x16x64_i8 v[64:67], v[164:167], v[204:207], v[64:67]
	v_mfma_i32_16x16x64_i8 v[108:111], v[160:163], v[184:187], v[108:111]
	v_mfma_i32_16x16x64_i8 v[100:103], v[168:171], v[184:187], v[100:103]
	v_mfma_i32_16x16x64_i8 v[92:95], v[160:163], v[192:195], v[92:95]
	v_mfma_i32_16x16x64_i8 v[84:87], v[168:171], v[192:195], v[84:87]
	v_mfma_i32_16x16x64_i8 v[76:79], v[160:163], v[200:203], v[76:79]
	v_mfma_i32_16x16x64_i8 v[72:75], v[168:171], v[200:203], v[72:75]
	v_mfma_i32_16x16x64_i8 v[68:71], v[160:163], v[208:211], v[68:71]
	v_mfma_i32_16x16x64_i8 v[64:67], v[168:171], v[208:211], v[64:67]
	s_setprio 0
	s_barrier
	s_add_i32 s40, s75, s42
	v_lshl_add_u64 v[172:173], v[172:173], 0, s[20:21]
	s_mov_b32 m0, s40
	ds_read_b128 v[180:183], v178 offset:49152
	ds_read_b128 v[184:187], v178 offset:50176
	ds_read_b128 v[188:191], v178 offset:51200
	ds_read_b128 v[192:195], v178 offset:52224
	global_load_lds_dwordx4 v[172:173], off
	s_add_i32 m0, s40, 0x2000
	s_add_u32 s38, s38, 0x80080
	v_lshl_add_u64 v[172:173], v[212:213], 0, s[20:21]
	s_addc_u32 s39, s39, 0
	s_add_i32 s40, s76, s42
	global_load_lds_dwordx4 v[172:173], off
	s_mov_b32 m0, s40
	ds_read_b128 v[208:211], v178 offset:56320
	global_load_lds_dwordx4 v130, s[38:39]
	s_add_i32 m0, s40, 0x2000
	ds_read_b128 v[204:207], v178 offset:55296
	global_load_lds_dwordx4 v134, s[38:39]
	v_lshl_add_u64 v[172:173], v[214:215], 0, s[20:21]
	s_mov_b32 m0, s51
	ds_read_b128 v[200:203], v178 offset:54272
	global_load_lds_dwordx4 v[172:173], off
	v_lshl_add_u64 v[172:173], v[216:217], 0, s[20:21]
	s_mov_b32 m0, s52
	ds_read_b128 v[196:199], v178 offset:53248
	global_load_lds_dwordx4 v[172:173], off
	s_waitcnt vmcnt(8)
	s_waitcnt lgkmcnt(0)
	s_barrier
	s_setprio 1
	s_waitcnt lgkmcnt(0)
	v_mfma_i32_16x16x64_i8 v[60:63], v[140:143], v[180:183], v[60:63]
	v_mfma_i32_16x16x64_i8 v[56:59], v[148:151], v[180:183], v[56:59]
	v_mfma_i32_16x16x64_i8 v[52:55], v[140:143], v[188:191], v[52:55]
	v_fmaak_f32 v226, v226, v220, 0x4b400000
	v_mfma_i32_16x16x64_i8 v[48:51], v[148:151], v[188:191], v[48:51]
	v_mfma_i32_16x16x64_i8 v[40:43], v[140:143], v[196:199], v[40:43]
	v_mfma_i32_16x16x64_i8 v[32:35], v[148:151], v[196:199], v[32:35]
	v_fmaak_f32 v227, v227, v225, 0x4b400000
	v_mfma_i32_16x16x64_i8 v[24:27], v[140:143], v[204:207], v[24:27]
	v_mfma_i32_16x16x64_i8 v[16:19], v[148:151], v[204:207], v[16:19]
	v_mfma_i32_16x16x64_i8 v[60:63], v[144:147], v[184:187], v[60:63]
	v_fmaak_f32 v228, v228, v252, 0x4b400000
	v_mfma_i32_16x16x64_i8 v[56:59], v[152:155], v[184:187], v[56:59]
	v_mfma_i32_16x16x64_i8 v[52:55], v[144:147], v[192:195], v[52:55]
	v_mfma_i32_16x16x64_i8 v[48:51], v[152:155], v[192:195], v[48:51]
	v_fmaak_f32 v229, v229, v253, 0x4b400000
	v_mfma_i32_16x16x64_i8 v[40:43], v[144:147], v[200:203], v[40:43]
	v_mfma_i32_16x16x64_i8 v[32:35], v[152:155], v[200:203], v[32:35]
	v_mfma_i32_16x16x64_i8 v[24:27], v[144:147], v[208:211], v[24:27]
	v_alignbit_b32 v239, v226, v239, 8
	v_mfma_i32_16x16x64_i8 v[16:19], v[152:155], v[208:211], v[16:19]
	s_setprio 0
	s_setprio 1
	v_mfma_i32_16x16x64_i8 v[44:47], v[156:159], v[180:183], v[44:47]
	v_mfma_i32_16x16x64_i8 v[36:39], v[164:167], v[180:183], v[36:39]
	v_alignbit_b32 v243, v227, v243, 8
	v_mfma_i32_16x16x64_i8 v[28:31], v[156:159], v[188:191], v[28:31]
	v_mfma_i32_16x16x64_i8 v[20:23], v[164:167], v[188:191], v[20:23]
	v_mfma_i32_16x16x64_i8 v[12:15], v[156:159], v[196:199], v[12:15]
	v_alignbit_b32 v247, v228, v247, 8
	v_mfma_i32_16x16x64_i8 v[8:11], v[164:167], v[196:199], v[8:11]
	v_mfma_i32_16x16x64_i8 v[4:7], v[156:159], v[204:207], v[4:7]
	v_mfma_i32_16x16x64_i8 v[0:3], v[164:167], v[204:207], v[0:3]
	v_alignbit_b32 v251, v229, v251, 8
	v_mfma_i32_16x16x64_i8 v[44:47], v[160:163], v[184:187], v[44:47]
	v_mfma_i32_16x16x64_i8 v[36:39], v[168:171], v[184:187], v[36:39]
	v_mfma_i32_16x16x64_i8 v[28:31], v[160:163], v[192:195], v[28:31]
	v_add_u32_e32 v223, 0x4000, v223
	v_mfma_i32_16x16x64_i8 v[20:23], v[168:171], v[192:195], v[20:23]
	v_mfma_i32_16x16x64_i8 v[12:15], v[160:163], v[200:203], v[12:15]
	v_mfma_i32_16x16x64_i8 v[8:11], v[168:171], v[200:203], v[8:11]
	v_mfma_i32_16x16x64_i8 v[4:7], v[160:163], v[208:211], v[4:7]
	v_mfma_i32_16x16x64_i8 v[0:3], v[168:171], v[208:211], v[0:3]
	s_setprio 0
	s_barrier
	s_cmp_eq_u32 s32, 0
	s_cbranch_scc1 .Lq_mvx_ST
	s_and_b32 s77, s84, 3
	s_cbranch_scc0 .Lq_mv_ST

.LBB0_1474:
	s_add_i32 s75, s48, 2
	s_add_u32 s46, s44, 0x100
	s_addc_u32 s47, s45, 0
	s_cmp_eq_u32 s72, s48
	s_cselect_b32 s51, s41, s47
	s_cselect_b32 s50, s40, s46
	ds_read_b128 v[140:143], v184
	ds_read_b128 v[144:147], v184 offset:1024
	ds_read_b128 v[148:151], v184 offset:2048
	ds_read_b128 v[152:155], v184 offset:3072
	ds_read_b128 v[156:159], v184 offset:16384
	ds_read_b128 v[160:163], v184 offset:17408
	ds_read_b128 v[164:167], v184 offset:18432
	ds_read_b128 v[168:171], v184 offset:19456
	s_cselect_b32 s48, s42, s73
	s_cselect_b32 s49, s43, s74
	s_add_i32 m0, s54, 0xc000
	ds_read_b128 v[172:175], v186
	ds_read_b128 v[176:179], v186 offset:1024
	ds_read_b128 v[188:191], v186 offset:2048
	ds_read_b128 v[192:195], v186 offset:3072
	ds_read_b128 v[196:199], v186 offset:4096
	ds_read_b128 v[200:203], v186 offset:5120
	ds_read_b128 v[204:207], v186 offset:6144
	global_load_lds_dwordx4 v136, s[44:45]
	s_add_i32 m0, s54, 0xe000
	ds_read_b128 v[208:211], v186 offset:7168
	global_load_lds_dwordx4 v138, s[44:45]
	s_waitcnt vmcnt(8)
	s_waitcnt lgkmcnt(0)
	s_barrier
	s_setprio 1
	s_waitcnt lgkmcnt(0)
	v_mfma_i32_16x16x64_i8 v[124:127], v[140:143], v[172:175], v[124:127]
	v_mfma_i32_16x16x64_i8 v[120:123], v[148:151], v[172:175], v[120:123]
	v_mfma_i32_16x16x64_i8 v[116:119], v[140:143], v[188:191], v[116:119]
	v_mfma_i32_16x16x64_i8 v[112:115], v[148:151], v[188:191], v[112:115]
	v_mfma_i32_16x16x64_i8 v[104:107], v[140:143], v[196:199], v[104:107]
	v_mfma_i32_16x16x64_i8 v[96:99], v[148:151], v[196:199], v[96:99]
	v_mfma_i32_16x16x64_i8 v[88:91], v[140:143], v[204:207], v[88:91]
	v_mfma_i32_16x16x64_i8 v[80:83], v[148:151], v[204:207], v[80:83]
	v_mfma_i32_16x16x64_i8 v[124:127], v[144:147], v[176:179], v[124:127]
	v_mfma_i32_16x16x64_i8 v[120:123], v[152:155], v[176:179], v[120:123]
	v_mfma_i32_16x16x64_i8 v[116:119], v[144:147], v[192:195], v[116:119]
	v_mfma_i32_16x16x64_i8 v[112:115], v[152:155], v[192:195], v[112:115]
	v_mfma_i32_16x16x64_i8 v[104:107], v[144:147], v[200:203], v[104:107]
	v_mfma_i32_16x16x64_i8 v[96:99], v[152:155], v[200:203], v[96:99]
	v_mfma_i32_16x16x64_i8 v[88:91], v[144:147], v[208:211], v[88:91]
	v_mfma_i32_16x16x64_i8 v[80:83], v[152:155], v[208:211], v[80:83]
	s_setprio 0
	s_setprio 1
	v_mfma_i32_16x16x64_i8 v[108:111], v[156:159], v[172:175], v[108:111]
	v_mfma_i32_16x16x64_i8 v[100:103], v[164:167], v[172:175], v[100:103]
	v_mfma_i32_16x16x64_i8 v[92:95], v[156:159], v[188:191], v[92:95]
	v_mfma_i32_16x16x64_i8 v[84:87], v[164:167], v[188:191], v[84:87]
	v_mfma_i32_16x16x64_i8 v[76:79], v[156:159], v[196:199], v[76:79]
	v_mfma_i32_16x16x64_i8 v[72:75], v[164:167], v[196:199], v[72:75]
	v_mfma_i32_16x16x64_i8 v[68:71], v[156:159], v[204:207], v[68:71]
	v_mfma_i32_16x16x64_i8 v[64:67], v[164:167], v[204:207], v[64:67]
	v_mfma_i32_16x16x64_i8 v[108:111], v[160:163], v[176:179], v[108:111]
	v_mfma_i32_16x16x64_i8 v[100:103], v[168:171], v[176:179], v[100:103]
	v_mfma_i32_16x16x64_i8 v[92:95], v[160:163], v[192:195], v[92:95]
	v_mfma_i32_16x16x64_i8 v[84:87], v[168:171], v[192:195], v[84:87]
	v_mfma_i32_16x16x64_i8 v[76:79], v[160:163], v[200:203], v[76:79]
	v_mfma_i32_16x16x64_i8 v[72:75], v[168:171], v[200:203], v[72:75]
	v_mfma_i32_16x16x64_i8 v[68:71], v[160:163], v[208:211], v[68:71]
	v_mfma_i32_16x16x64_i8 v[64:67], v[168:171], v[208:211], v[64:67]
	s_setprio 0
	s_barrier
	s_add_i32 s44, s66, s53
	s_mov_b32 m0, s44
	ds_read_b128 v[172:175], v186 offset:16384
	ds_read_b128 v[176:179], v186 offset:17408
	ds_read_b128 v[188:191], v186 offset:18432
	ds_read_b128 v[192:195], v186 offset:19456
	global_load_lds_dwordx4 v130, s[48:49]
	s_add_i32 m0, s44, 0x2000
	s_add_u32 s44, s48, 0x158000
	s_addc_u32 s45, s49, 0
	s_add_i32 s76, s67, s53
	global_load_lds_dwordx4 v134, s[48:49]
	s_mov_b32 m0, s76
	ds_read_b128 v[208:211], v186 offset:23552
	global_load_lds_dwordx4 v130, s[44:45]
	s_add_i32 m0, s76, 0x2000
	ds_read_b128 v[204:207], v186 offset:22528
	global_load_lds_dwordx4 v134, s[44:45]
	s_mov_b32 m0, s54
	ds_read_b128 v[200:203], v186 offset:21504
	global_load_lds_dwordx4 v128, s[50:51]
	s_mov_b32 m0, s55
	ds_read_b128 v[196:199], v186 offset:20480
	global_load_lds_dwordx4 v132, s[50:51]
	s_waitcnt vmcnt(8)
	s_waitcnt lgkmcnt(0)
	s_barrier
	s_setprio 1
	s_waitcnt lgkmcnt(0)
	v_mfma_i32_16x16x64_i8 v[60:63], v[140:143], v[172:175], v[60:63]
	v_mfma_i32_16x16x64_i8 v[56:59], v[148:151], v[172:175], v[56:59]
	v_mfma_i32_16x16x64_i8 v[52:55], v[140:143], v[188:191], v[52:55]
	v_mfma_i32_16x16x64_i8 v[48:51], v[148:151], v[188:191], v[48:51]
	v_mfma_i32_16x16x64_i8 v[40:43], v[140:143], v[196:199], v[40:43]
	v_mfma_i32_16x16x64_i8 v[32:35], v[148:151], v[196:199], v[32:35]
	v_mfma_i32_16x16x64_i8 v[24:27], v[140:143], v[204:207], v[24:27]
	v_mfma_i32_16x16x64_i8 v[16:19], v[148:151], v[204:207], v[16:19]
	v_mfma_i32_16x16x64_i8 v[60:63], v[144:147], v[176:179], v[60:63]
	v_mfma_i32_16x16x64_i8 v[56:59], v[152:155], v[176:179], v[56:59]
	v_mfma_i32_16x16x64_i8 v[52:55], v[144:147], v[192:195], v[52:55]
	v_mfma_i32_16x16x64_i8 v[48:51], v[152:155], v[192:195], v[48:51]
	v_mfma_i32_16x16x64_i8 v[40:43], v[144:147], v[200:203], v[40:43]
	v_mfma_i32_16x16x64_i8 v[32:35], v[152:155], v[200:203], v[32:35]
	v_mfma_i32_16x16x64_i8 v[24:27], v[144:147], v[208:211], v[24:27]
	v_mfma_i32_16x16x64_i8 v[16:19], v[152:155], v[208:211], v[16:19]
	s_setprio 0
	s_setprio 1
	v_mfma_i32_16x16x64_i8 v[44:47], v[156:159], v[172:175], v[44:47]
	v_mfma_i32_16x16x64_i8 v[36:39], v[164:167], v[172:175], v[36:39]
	v_mfma_i32_16x16x64_i8 v[28:31], v[156:159], v[188:191], v[28:31]
	v_mfma_i32_16x16x64_i8 v[20:23], v[164:167], v[188:191], v[20:23]
	v_mfma_i32_16x16x64_i8 v[12:15], v[156:159], v[196:199], v[12:15]
	v_mfma_i32_16x16x64_i8 v[8:11], v[164:167], v[196:199], v[8:11]
	v_mfma_i32_16x16x64_i8 v[4:7], v[156:159], v[204:207], v[4:7]
	v_mfma_i32_16x16x64_i8 v[0:3], v[164:167], v[204:207], v[0:3]
	v_mfma_i32_16x16x64_i8 v[44:47], v[160:163], v[176:179], v[44:47]
	v_mfma_i32_16x16x64_i8 v[36:39], v[168:171], v[176:179], v[36:39]
	v_mfma_i32_16x16x64_i8 v[28:31], v[160:163], v[192:195], v[28:31]
	v_mfma_i32_16x16x64_i8 v[20:23], v[168:171], v[192:195], v[20:23]
	v_mfma_i32_16x16x64_i8 v[12:15], v[160:163], v[200:203], v[12:15]
	v_mfma_i32_16x16x64_i8 v[8:11], v[168:171], v[200:203], v[8:11]
	v_mfma_i32_16x16x64_i8 v[4:7], v[160:163], v[208:211], v[4:7]
	v_mfma_i32_16x16x64_i8 v[0:3], v[168:171], v[208:211], v[0:3]
	s_setprio 0
	s_barrier
	s_add_i32 s76, 0, 0x18000
	s_add_i32 s77, 0, 0x1c000
	ds_read_b128 v[140:143], v184 offset:32768
	ds_read_b128 v[144:147], v184 offset:33792
	ds_read_b128 v[148:151], v184 offset:34816
	ds_read_b128 v[152:155], v184 offset:35840
	ds_read_b128 v[156:159], v184 offset:49152
	ds_read_b128 v[160:163], v184 offset:50176
	ds_read_b128 v[164:167], v184 offset:51200
	ds_read_b128 v[168:171], v184 offset:52224
	s_add_u32 s44, s50, 0x158000
	s_addc_u32 s45, s51, 0
	s_mov_b32 m0, s60
	ds_read_b128 v[172:175], v186 offset:32768
	ds_read_b128 v[176:179], v186 offset:33792
	ds_read_b128 v[188:191], v186 offset:34816
	ds_read_b128 v[192:195], v186 offset:35840
	ds_read_b128 v[196:199], v186 offset:36864
	ds_read_b128 v[200:203], v186 offset:37888
	ds_read_b128 v[204:207], v186 offset:38912
	global_load_lds_dwordx4 v128, s[44:45]
	s_mov_b32 m0, s61
	ds_read_b128 v[208:211], v186 offset:39936
	global_load_lds_dwordx4 v132, s[44:45]
	s_waitcnt vmcnt(8)
	s_waitcnt lgkmcnt(0)
	s_barrier
	s_setprio 1
	s_waitcnt lgkmcnt(0)
	v_mfma_i32_16x16x64_i8 v[124:127], v[140:143], v[172:175], v[124:127]
	v_mfma_i32_16x16x64_i8 v[120:123], v[148:151], v[172:175], v[120:123]
	v_mfma_i32_16x16x64_i8 v[116:119], v[140:143], v[188:191], v[116:119]
	v_mfma_i32_16x16x64_i8 v[112:115], v[148:151], v[188:191], v[112:115]
	v_mfma_i32_16x16x64_i8 v[104:107], v[140:143], v[196:199], v[104:107]
	v_mfma_i32_16x16x64_i8 v[96:99], v[148:151], v[196:199], v[96:99]
	v_mfma_i32_16x16x64_i8 v[88:91], v[140:143], v[204:207], v[88:91]
	v_mfma_i32_16x16x64_i8 v[80:83], v[148:151], v[204:207], v[80:83]
	v_mfma_i32_16x16x64_i8 v[124:127], v[144:147], v[176:179], v[124:127]
	v_mfma_i32_16x16x64_i8 v[120:123], v[152:155], v[176:179], v[120:123]
	v_mfma_i32_16x16x64_i8 v[116:119], v[144:147], v[192:195], v[116:119]
	v_mfma_i32_16x16x64_i8 v[112:115], v[152:155], v[192:195], v[112:115]
	v_mfma_i32_16x16x64_i8 v[104:107], v[144:147], v[200:203], v[104:107]
	v_mfma_i32_16x16x64_i8 v[96:99], v[152:155], v[200:203], v[96:99]
	v_mfma_i32_16x16x64_i8 v[88:91], v[144:147], v[208:211], v[88:91]
	v_mfma_i32_16x16x64_i8 v[80:83], v[152:155], v[208:211], v[80:83]
	s_setprio 0
	s_setprio 1
	v_mfma_i32_16x16x64_i8 v[108:111], v[156:159], v[172:175], v[108:111]
	v_mfma_i32_16x16x64_i8 v[100:103], v[164:167], v[172:175], v[100:103]
	v_mfma_i32_16x16x64_i8 v[92:95], v[156:159], v[188:191], v[92:95]
	v_mfma_i32_16x16x64_i8 v[84:87], v[164:167], v[188:191], v[84:87]
	v_mfma_i32_16x16x64_i8 v[76:79], v[156:159], v[196:199], v[76:79]
	v_mfma_i32_16x16x64_i8 v[72:75], v[164:167], v[196:199], v[72:75]
	v_mfma_i32_16x16x64_i8 v[68:71], v[156:159], v[204:207], v[68:71]
	v_mfma_i32_16x16x64_i8 v[64:67], v[164:167], v[204:207], v[64:67]
	v_mfma_i32_16x16x64_i8 v[108:111], v[160:163], v[176:179], v[108:111]
	v_mfma_i32_16x16x64_i8 v[100:103], v[168:171], v[176:179], v[100:103]
	v_mfma_i32_16x16x64_i8 v[92:95], v[160:163], v[192:195], v[92:95]
	v_mfma_i32_16x16x64_i8 v[84:87], v[168:171], v[192:195], v[84:87]
	v_mfma_i32_16x16x64_i8 v[76:79], v[160:163], v[200:203], v[76:79]
	v_mfma_i32_16x16x64_i8 v[72:75], v[168:171], v[200:203], v[72:75]
	v_mfma_i32_16x16x64_i8 v[68:71], v[160:163], v[208:211], v[68:71]
	v_mfma_i32_16x16x64_i8 v[64:67], v[168:171], v[208:211], v[64:67]
	s_setprio 0
	s_barrier
	s_add_u32 s98, s48, s18
	s_addc_u32 s99, s49, s19
	s_add_u32 s100, s50, s18
	s_addc_u32 s101, s51, s19
	s_add_i32 s44, s76, s53
	s_mov_b32 m0, s44
	ds_read_b128 v[172:175], v186 offset:49152
	ds_read_b128 v[176:179], v186 offset:50176
	ds_read_b128 v[188:191], v186 offset:51200
	ds_read_b128 v[192:195], v186 offset:52224
	global_load_lds_dwordx4 v130, s[98:99]
	s_add_i32 m0, s44, 0x2000
	s_add_u32 s44, s48, 0x158080
	s_addc_u32 s45, s49, 0
	s_add_i32 s48, s77, s53
	global_load_lds_dwordx4 v134, s[98:99]
	s_mov_b32 m0, s48
	ds_read_b128 v[208:211], v186 offset:56320
	global_load_lds_dwordx4 v130, s[44:45]
	s_add_i32 m0, s48, 0x2000
	ds_read_b128 v[204:207], v186 offset:55296
	global_load_lds_dwordx4 v134, s[44:45]
	s_mov_b32 m0, s64
	ds_read_b128 v[200:203], v186 offset:54272
	global_load_lds_dwordx4 v128, s[100:101]
	s_mov_b32 m0, s65
	ds_read_b128 v[196:199], v186 offset:53248
	global_load_lds_dwordx4 v132, s[100:101]
	s_waitcnt vmcnt(8)
	s_waitcnt lgkmcnt(0)
	s_barrier
	s_setprio 1
	s_waitcnt lgkmcnt(0)
	v_mfma_i32_16x16x64_i8 v[60:63], v[140:143], v[172:175], v[60:63]
	v_mfma_i32_16x16x64_i8 v[56:59], v[148:151], v[172:175], v[56:59]
	v_mfma_i32_16x16x64_i8 v[52:55], v[140:143], v[188:191], v[52:55]
	v_mfma_i32_16x16x64_i8 v[48:51], v[148:151], v[188:191], v[48:51]
	v_mfma_i32_16x16x64_i8 v[40:43], v[140:143], v[196:199], v[40:43]
	v_mfma_i32_16x16x64_i8 v[32:35], v[148:151], v[196:199], v[32:35]
	v_mfma_i32_16x16x64_i8 v[24:27], v[140:143], v[204:207], v[24:27]
	v_mfma_i32_16x16x64_i8 v[16:19], v[148:151], v[204:207], v[16:19]
	v_mfma_i32_16x16x64_i8 v[60:63], v[144:147], v[176:179], v[60:63]
	v_mfma_i32_16x16x64_i8 v[56:59], v[152:155], v[176:179], v[56:59]
	v_mfma_i32_16x16x64_i8 v[52:55], v[144:147], v[192:195], v[52:55]
	v_mfma_i32_16x16x64_i8 v[48:51], v[152:155], v[192:195], v[48:51]
	v_mfma_i32_16x16x64_i8 v[40:43], v[144:147], v[200:203], v[40:43]
	v_mfma_i32_16x16x64_i8 v[32:35], v[152:155], v[200:203], v[32:35]
	v_mfma_i32_16x16x64_i8 v[24:27], v[144:147], v[208:211], v[24:27]
	v_mfma_i32_16x16x64_i8 v[16:19], v[152:155], v[208:211], v[16:19]
	s_setprio 0
	s_setprio 1
	v_mfma_i32_16x16x64_i8 v[44:47], v[156:159], v[172:175], v[44:47]
	v_mfma_i32_16x16x64_i8 v[36:39], v[164:167], v[172:175], v[36:39]
	v_mfma_i32_16x16x64_i8 v[28:31], v[156:159], v[188:191], v[28:31]
	v_mfma_i32_16x16x64_i8 v[20:23], v[164:167], v[188:191], v[20:23]
	v_mfma_i32_16x16x64_i8 v[12:15], v[156:159], v[196:199], v[12:15]
	v_mfma_i32_16x16x64_i8 v[8:11], v[164:167], v[196:199], v[8:11]
	v_mfma_i32_16x16x64_i8 v[4:7], v[156:159], v[204:207], v[4:7]
	v_mfma_i32_16x16x64_i8 v[0:3], v[164:167], v[204:207], v[0:3]
	v_mfma_i32_16x16x64_i8 v[44:47], v[160:163], v[176:179], v[44:47]
	v_mfma_i32_16x16x64_i8 v[36:39], v[168:171], v[176:179], v[36:39]
	v_mfma_i32_16x16x64_i8 v[28:31], v[160:163], v[192:195], v[28:31]
	v_mfma_i32_16x16x64_i8 v[20:23], v[168:171], v[192:195], v[20:23]
	v_mfma_i32_16x16x64_i8 v[12:15], v[160:163], v[200:203], v[12:15]
	v_mfma_i32_16x16x64_i8 v[8:11], v[168:171], v[200:203], v[8:11]
	v_mfma_i32_16x16x64_i8 v[4:7], v[160:163], v[208:211], v[4:7]
	v_mfma_i32_16x16x64_i8 v[0:3], v[168:171], v[208:211], v[0:3]
	s_setprio 0
	s_barrier
	s_add_u32 s73, s73, 0x100
	s_addc_u32 s74, s74, 0
	s_cmp_ge_i32 s75, s71
	s_mov_b64 s[44:45], s[46:47]
	s_mov_b32 s48, s75
	s_cbranch_scc0 .LBB0_1474
	v_cvt_f32_i32_e32 v140, v124
	v_cvt_f32_i32_e32 v141, v125
	v_cvt_f32_i32_e32 v124, v126
	v_cvt_f32_i32_e32 v125, v127
	v_cvt_f32_i32_e32 v142, v120
	v_cvt_f32_i32_e32 v143, v121
	v_cvt_f32_i32_e32 v126, v122
	v_cvt_f32_i32_e32 v127, v123
	v_cvt_f32_i32_e32 v146, v108
	v_cvt_f32_i32_e32 v147, v109
	v_cvt_f32_i32_e32 v120, v110
	v_cvt_f32_i32_e32 v121, v111
	v_cvt_f32_i32_e32 v148, v100
	v_cvt_f32_i32_e32 v149, v101
	v_cvt_f32_i32_e32 v122, v102
	v_cvt_f32_i32_e32 v123, v103
	v_cvt_f32_i32_e32 v144, v116
	v_cvt_f32_i32_e32 v145, v117
	v_cvt_f32_i32_e32 v116, v118
	v_cvt_f32_i32_e32 v117, v119
	v_cvt_f32_i32_e32 v118, v112
	v_cvt_f32_i32_e32 v119, v113
	v_cvt_f32_i32_e32 v112, v114
	v_cvt_f32_i32_e32 v113, v115
	v_cvt_f32_i32_e32 v152, v92
	v_cvt_f32_i32_e32 v153, v93
	v_cvt_f32_i32_e32 v100, v94
	v_cvt_f32_i32_e32 v101, v95
	v_cvt_f32_i32_e32 v156, v84
	v_cvt_f32_i32_e32 v157, v85
	v_cvt_f32_i32_e32 v102, v86
	v_cvt_f32_i32_e32 v103, v87
	v_cvt_f32_i32_e32 v114, v104
	v_cvt_f32_i32_e32 v115, v105
	v_cvt_f32_i32_e32 v86, v106
	v_cvt_f32_i32_e32 v87, v107
	v_cvt_f32_i32_e32 v150, v96
	v_cvt_f32_i32_e32 v151, v97
	v_cvt_f32_i32_e32 v92, v98
	v_cvt_f32_i32_e32 v93, v99
	v_cvt_f32_i32_e32 v160, v76
	v_cvt_f32_i32_e32 v161, v77
	v_cvt_f32_i32_e32 v84, v78
	v_cvt_f32_i32_e32 v85, v79
	v_cvt_f32_i32_e32 v162, v72
	v_cvt_f32_i32_e32 v163, v73
	v_cvt_f32_i32_e32 v94, v74
	v_cvt_f32_i32_e32 v95, v75
	v_cvt_f32_i32_e32 v154, v88
	v_cvt_f32_i32_e32 v155, v89
	v_cvt_f32_i32_e32 v78, v90
	v_cvt_f32_i32_e32 v79, v91
	v_cvt_f32_i32_e32 v158, v80
	v_cvt_f32_i32_e32 v159, v81
	v_cvt_f32_i32_e32 v80, v82
	v_cvt_f32_i32_e32 v81, v83
	v_cvt_f32_i32_e32 v164, v68
	v_cvt_f32_i32_e32 v165, v69
	v_cvt_f32_i32_e32 v76, v70
	v_cvt_f32_i32_e32 v77, v71
	v_cvt_f32_i32_e32 v166, v64
	v_cvt_f32_i32_e32 v167, v65
	v_cvt_f32_i32_e32 v82, v66
	v_cvt_f32_i32_e32 v83, v67
	v_cvt_f32_i32_e32 v70, v60
	v_cvt_f32_i32_e32 v71, v61
	v_cvt_f32_i32_e32 v74, v62
	v_cvt_f32_i32_e32 v75, v63
	v_cvt_f32_i32_e32 v68, v56
	v_cvt_f32_i32_e32 v69, v57
	v_cvt_f32_i32_e32 v72, v58
	v_cvt_f32_i32_e32 v73, v59
	v_cvt_f32_i32_e32 v62, v44
	v_cvt_f32_i32_e32 v63, v45
	v_cvt_f32_i32_e32 v66, v46
	v_cvt_f32_i32_e32 v67, v47
	v_cvt_f32_i32_e32 v60, v36
	v_cvt_f32_i32_e32 v61, v37
	v_cvt_f32_i32_e32 v64, v38
	v_cvt_f32_i32_e32 v65, v39
	v_cvt_f32_i32_e32 v56, v52
	v_cvt_f32_i32_e32 v57, v53
	v_cvt_f32_i32_e32 v58, v54
	v_cvt_f32_i32_e32 v59, v55
	v_cvt_f32_i32_e32 v52, v48
	v_cvt_f32_i32_e32 v53, v49
	v_cvt_f32_i32_e32 v54, v50
	v_cvt_f32_i32_e32 v55, v51
	v_cvt_f32_i32_e32 v46, v28
	v_cvt_f32_i32_e32 v47, v29
	v_cvt_f32_i32_e32 v50, v30
	v_cvt_f32_i32_e32 v51, v31
	v_cvt_f32_i32_e32 v44, v20
	v_cvt_f32_i32_e32 v45, v21
	v_cvt_f32_i32_e32 v48, v22
	v_cvt_f32_i32_e32 v49, v23
	v_cvt_f32_i32_e32 v38, v40
	v_cvt_f32_i32_e32 v39, v41
	v_cvt_f32_i32_e32 v42, v42
	v_cvt_f32_i32_e32 v43, v43
	v_cvt_f32_i32_e32 v36, v32
	v_cvt_f32_i32_e32 v37, v33
	v_cvt_f32_i32_e32 v40, v34
	v_cvt_f32_i32_e32 v41, v35
	v_cvt_f32_i32_e32 v30, v12
	v_cvt_f32_i32_e32 v31, v13
	v_cvt_f32_i32_e32 v34, v14
	v_cvt_f32_i32_e32 v35, v15
	v_cvt_f32_i32_e32 v28, v8
	v_cvt_f32_i32_e32 v29, v9
	v_cvt_f32_i32_e32 v32, v10
	v_cvt_f32_i32_e32 v33, v11
	v_cvt_f32_i32_e32 v22, v24
	v_cvt_f32_i32_e32 v23, v25
	v_cvt_f32_i32_e32 v26, v26
	v_cvt_f32_i32_e32 v27, v27
	v_cvt_f32_i32_e32 v20, v16
	v_cvt_f32_i32_e32 v21, v17
	v_cvt_f32_i32_e32 v24, v18
	v_cvt_f32_i32_e32 v25, v19
	v_cvt_f32_i32_e32 v14, v4
	v_cvt_f32_i32_e32 v15, v5
	v_cvt_f32_i32_e32 v18, v6
	v_cvt_f32_i32_e32 v19, v7
	v_cvt_f32_i32_e32 v12, v0
	v_cvt_f32_i32_e32 v13, v1
	v_cvt_f32_i32_e32 v16, v2
	v_cvt_f32_i32_e32 v17, v3
	s_and_b64 vcc, exec, s[20:21]
	s_cbranch_vccz .LBB0_1477
